# out-projection fused epilogue: non-temporal hint on the once-read f32 residual loads
# speedup vs baseline: 1.0016x; 1.0016x over previous
; __device__ __forceinline__ unsigned cvt_pk_bf16(float lo, float hi) { unsigned r; asm volatile("v_cvt_pk_bf16_f32 %0, %1, %2" : "=v"(r) : "v"(lo), "v"(hi)); return r; }
;     __device__ __forceinline__ void fused(f32x4 (&acc)[2][2][4][2], const Unit& u, int wr, int wc, int fr, int fq, LAS unsigned char* lds, int wid, int lane) const {
;         const int row0 = u.pm * BM + wr * 64 + fr, col0 = u.pn * BM + wc * 32 + 4 * fq, b = u.pm >> 3;
;         const float* modb = mod + (size_t)b * NMOD + col0;
;         { f32x4 gv[2][2];
; #pragma unroll
;           for (int bj = 0; bj < 2; ++bj)
; #pragma unroll
;             for (int n = 0; n < 2; ++n) gv[bj][n] = *(const f32x4*)(modb + gate_off + bj * HALF + n * 16);
; #pragma unroll
;           for (int ai = 0; ai < 2; ++ai)
; #pragma unroll
;             for (int m = 0; m < 4; ++m) { const size_t off = (size_t)(row0 + ai * HALF + m * 16) * DM + col0;
; #pragma unroll
;                 for (int bj = 0; bj < 2; ++bj)
; #pragma unroll
;                     for (int n = 0; n < 2; ++n) { const f32x4 xv = *(const f32x4*)(base + off + bj * HALF + n * 16); const f32x4 o = xv + gv[bj][n] * acc[ai][bj][m][n];
;                         u32x2 w; w.x = cvt_pk_bf16(o[0], o[1]); w.y = cvt_pk_bf16(o[2], o[3]); *(u32x2*)(x1b + off + bj * HALF + n * 16) = w; acc[ai][bj][m][n] = o; }
;                 asm volatile("" ::: "memory"); } }
.LBB0_582:
	s_add_u32 s0, s34, 0xd200000
	s_addc_u32 s1, s35, 0
	s_lshl_b32 s11, s7, 5
	s_lshl_b32 s12, s8, 8
	s_or_b32 s11, s12, s11
	s_lshl_b32 s10, s6, 8
	v_and_or_b32 v144, v140, 12, s11
	s_ashr_i32 s11, s6, 3
	s_add_i32 s14, s10, s54
	s_mul_hi_i32 s13, s11, 0x6000
	s_mulk_i32 s11, 0x6000
	s_add_u32 s12, s34, s11
	v_or_b32_e32 v150, s14, v153
	s_addc_u32 s13, s35, s13
	v_ashrrev_i32_e32 v145, 31, v144
	v_ashrrev_i32_e32 v151, 31, v150
	v_lshl_add_u64 v[146:147], v[144:145], 2, s[12:13]
	s_movk_i32 s11, 0x2000
	v_lshlrev_b64 v[130:131], 10, v[150:151]
	v_add_co_u32_e32 v128, vcc, s11, v146
	v_lshl_add_u64 v[148:149], v[130:131], 0, v[144:145]
	s_nop 0
	v_addc_co_u32_e32 v129, vcc, 0, v147, vcc
	v_lshl_add_u64 v[158:159], v[148:149], 2, s[36:37]
	s_barrier
	global_load_dwordx4 v[154:157], v[158:159], off nt
	global_load_dwordx4 v[140:143], v[128:129], off
	global_load_dwordx4 v[136:139], v[128:129], off offset:64
	global_load_dwordx4 v[132:135], v[128:129], off offset:512
	s_nop 0
	global_load_dwordx4 v[128:131], v[128:129], off offset:576
	v_lshl_add_u64 v[160:161], v[148:149], 1, s[0:1]
	s_mov_b64 s[12:13], 0x20000
	s_waitcnt vmcnt(0)
	v_pk_fma_f32 v[126:127], v[126:127], v[142:143], v[156:157]
	v_pk_fma_f32 v[124:125], v[124:125], v[140:141], v[154:155]
	s_nop 0
	v_cvt_pk_bf16_f32 v154, v124, v125
	v_cvt_pk_bf16_f32 v155, v126, v127
	global_store_dwordx2 v[160:161], v[154:155], off
	global_load_dwordx4 v[154:157], v[158:159], off offset:64 nt
	s_waitcnt vmcnt(0)
	v_pk_fma_f32 v[122:123], v[122:123], v[138:139], v[156:157]
	v_pk_fma_f32 v[120:121], v[120:121], v[136:137], v[154:155]
	s_nop 0
	v_cvt_pk_bf16_f32 v154, v120, v121
	v_cvt_pk_bf16_f32 v155, v122, v123
	global_store_dwordx2 v[160:161], v[154:155], off offset:32
	global_load_dwordx4 v[154:157], v[158:159], off offset:512 nt
	s_waitcnt vmcnt(0)
	v_pk_fma_f32 v[118:119], v[118:119], v[134:135], v[156:157]
	v_pk_fma_f32 v[116:117], v[116:117], v[132:133], v[154:155]
	s_nop 0
	v_cvt_pk_bf16_f32 v154, v116, v117
	v_cvt_pk_bf16_f32 v155, v118, v119
	global_store_dwordx2 v[160:161], v[154:155], off offset:256
	global_load_dwordx4 v[154:157], v[158:159], off offset:576 nt
	v_or_b32_e32 v158, 16, v150
	v_ashrrev_i32_e32 v159, 31, v158
	v_lshlrev_b64 v[158:159], 10, v[158:159]
	v_lshl_add_u64 v[158:159], v[158:159], 0, v[144:145]
	v_lshl_add_u64 v[162:163], v[158:159], 2, s[36:37]
	v_lshl_add_u64 v[158:159], v[158:159], 1, s[0:1]
	s_waitcnt vmcnt(0)
	v_pk_fma_f32 v[110:111], v[110:111], v[130:131], v[156:157]
	v_pk_fma_f32 v[108:109], v[108:109], v[128:129], v[154:155]
	s_nop 0
	v_cvt_pk_bf16_f32 v154, v108, v109
	v_cvt_pk_bf16_f32 v155, v110, v111
	global_store_dwordx2 v[160:161], v[154:155], off offset:288
	global_load_dwordx4 v[154:157], v[162:163], off nt
	v_or_b32_e32 v160, 32, v150
	v_ashrrev_i32_e32 v161, 31, v160
	v_lshlrev_b64 v[160:161], 10, v[160:161]
	v_lshl_add_u64 v[160:161], v[160:161], 0, v[144:145]
	v_or_b32_e32 v150, 48, v150
	v_ashrrev_i32_e32 v151, 31, v150
	v_lshlrev_b64 v[150:151], 10, v[150:151]
	v_lshl_add_u64 v[150:151], v[150:151], 0, v[144:145]
	s_waitcnt vmcnt(0)
	v_pk_fma_f32 v[114:115], v[114:115], v[142:143], v[156:157]
	v_pk_fma_f32 v[112:113], v[112:113], v[140:141], v[154:155]
	s_nop 0
	v_cvt_pk_bf16_f32 v154, v112, v113
	v_cvt_pk_bf16_f32 v155, v114, v115
	global_store_dwordx2 v[158:159], v[154:155], off
	global_load_dwordx4 v[154:157], v[162:163], off offset:64 nt
	s_waitcnt vmcnt(0)
	v_pk_fma_f32 v[106:107], v[106:107], v[138:139], v[156:157]
	v_pk_fma_f32 v[104:105], v[104:105], v[136:137], v[154:155]
	s_nop 0
	v_cvt_pk_bf16_f32 v154, v104, v105
	v_cvt_pk_bf16_f32 v155, v106, v107
	global_store_dwordx2 v[158:159], v[154:155], off offset:32
	global_load_dwordx4 v[154:157], v[162:163], off offset:512 nt
	s_waitcnt vmcnt(0)
	v_pk_fma_f32 v[102:103], v[102:103], v[134:135], v[156:157]
	v_pk_fma_f32 v[100:101], v[100:101], v[132:133], v[154:155]
	s_nop 0
	v_cvt_pk_bf16_f32 v154, v100, v101
	v_cvt_pk_bf16_f32 v155, v102, v103
	global_store_dwordx2 v[158:159], v[154:155], off offset:256
	global_load_dwordx4 v[154:157], v[162:163], off offset:576 nt
	v_lshl_add_u64 v[162:163], v[160:161], 2, s[36:37]
	s_waitcnt vmcnt(0)
	v_pk_fma_f32 v[94:95], v[94:95], v[130:131], v[156:157]
	v_pk_fma_f32 v[92:93], v[92:93], v[128:129], v[154:155]
	s_nop 0
	v_cvt_pk_bf16_f32 v154, v92, v93
	v_cvt_pk_bf16_f32 v155, v94, v95
	global_store_dwordx2 v[158:159], v[154:155], off offset:288
	global_load_dwordx4 v[154:157], v[162:163], off nt
	v_lshl_add_u64 v[158:159], v[160:161], 1, s[0:1]
	v_lshl_add_u64 v[160:161], v[150:151], 2, s[36:37]
	v_lshl_add_u64 v[150:151], v[150:151], 1, s[0:1]
	s_waitcnt vmcnt(0)
	v_pk_fma_f32 v[98:99], v[98:99], v[142:143], v[156:157]
	v_pk_fma_f32 v[96:97], v[96:97], v[140:141], v[154:155]
	s_nop 0
	v_cvt_pk_bf16_f32 v154, v96, v97
	v_cvt_pk_bf16_f32 v155, v98, v99
	global_store_dwordx2 v[158:159], v[154:155], off
	global_load_dwordx4 v[154:157], v[162:163], off offset:64 nt
	s_waitcnt vmcnt(0)
	v_pk_fma_f32 v[90:91], v[90:91], v[138:139], v[156:157]
	v_pk_fma_f32 v[88:89], v[88:89], v[136:137], v[154:155]
	s_nop 0
	v_cvt_pk_bf16_f32 v154, v88, v89
	v_cvt_pk_bf16_f32 v155, v90, v91
	global_store_dwordx2 v[158:159], v[154:155], off offset:32
	global_load_dwordx4 v[154:157], v[162:163], off offset:512 nt
	s_waitcnt vmcnt(0)
	v_pk_fma_f32 v[86:87], v[86:87], v[134:135], v[156:157]
	v_pk_fma_f32 v[84:85], v[84:85], v[132:133], v[154:155]
	s_nop 0
	v_cvt_pk_bf16_f32 v154, v84, v85
	v_cvt_pk_bf16_f32 v155, v86, v87
	global_store_dwordx2 v[158:159], v[154:155], off offset:256
	global_load_dwordx4 v[154:157], v[162:163], off offset:576 nt
	s_waitcnt vmcnt(0)
; __device__ __forceinline__ unsigned cvt_pk_bf16(float lo, float hi) { unsigned r; asm volatile("v_cvt_pk_bf16_f32 %0, %1, %2" : "=v"(r) : "v"(lo), "v"(hi)); return r; }
;     __device__ __forceinline__ void fused(f32x4 (&acc)[2][2][4][2], const Unit& u, int wr, int wc, int fr, int fq, LAS unsigned char* lds, int wid, int lane) const {
;     ...
;           for (int ai = 0; ai < 2; ++ai)
; #pragma unroll
;             for (int m = 0; m < 4; ++m) { const size_t off = (size_t)(row0 + ai * HALF + m * 16) * DM + col0;
; #pragma unroll
;                 for (int bj = 0; bj < 2; ++bj)
; #pragma unroll
;                     for (int n = 0; n < 2; ++n) { const f32x4 xv = *(const f32x4*)(base + off + bj * HALF + n * 16); const f32x4 o = xv + gv[bj][n] * acc[ai][bj][m][n];
;                         u32x2 w; w.x = cvt_pk_bf16(o[0], o[1]); w.y = cvt_pk_bf16(o[2], o[3]); *(u32x2*)(x1b + off + bj * HALF + n * 16) = w; acc[ai][bj][m][n] = o; }
;                 asm volatile("" ::: "memory"); } }
	v_pk_fma_f32 v[78:79], v[78:79], v[130:131], v[156:157]
	v_pk_fma_f32 v[76:77], v[76:77], v[128:129], v[154:155]
	s_nop 0
	v_cvt_pk_bf16_f32 v154, v76, v77
	v_cvt_pk_bf16_f32 v155, v78, v79
	global_store_dwordx2 v[158:159], v[154:155], off offset:288
	global_load_dwordx4 v[154:157], v[160:161], off nt
	v_lshl_add_u64 v[158:159], v[148:149], 0, s[12:13]
	s_mov_b64 s[12:13], 0x24000
	s_waitcnt vmcnt(0)
	v_pk_fma_f32 v[82:83], v[82:83], v[142:143], v[156:157]
	v_pk_fma_f32 v[80:81], v[80:81], v[140:141], v[154:155]
	s_nop 0
	v_cvt_pk_bf16_f32 v154, v80, v81
	v_cvt_pk_bf16_f32 v155, v82, v83
	global_store_dwordx2 v[150:151], v[154:155], off
	global_load_dwordx4 v[154:157], v[160:161], off offset:64 nt
	s_waitcnt vmcnt(0)
	v_pk_fma_f32 v[74:75], v[74:75], v[138:139], v[156:157]
	v_pk_fma_f32 v[72:73], v[72:73], v[136:137], v[154:155]
	s_nop 0
	v_cvt_pk_bf16_f32 v154, v72, v73
	v_cvt_pk_bf16_f32 v155, v74, v75
	global_store_dwordx2 v[150:151], v[154:155], off offset:32
	global_load_dwordx4 v[154:157], v[160:161], off offset:512 nt
	s_waitcnt vmcnt(0)
	v_pk_fma_f32 v[70:71], v[70:71], v[134:135], v[156:157]
	v_pk_fma_f32 v[68:69], v[68:69], v[132:133], v[154:155]
	s_nop 0
	v_cvt_pk_bf16_f32 v154, v68, v69
	v_cvt_pk_bf16_f32 v155, v70, v71
	global_store_dwordx2 v[150:151], v[154:155], off offset:256
	global_load_dwordx4 v[154:157], v[160:161], off offset:576 nt
	v_lshl_add_u64 v[160:161], v[158:159], 2, s[36:37]
	s_waitcnt vmcnt(0)
	v_pk_fma_f32 v[66:67], v[66:67], v[130:131], v[156:157]
	v_pk_fma_f32 v[64:65], v[64:65], v[128:129], v[154:155]
	s_nop 0
	v_cvt_pk_bf16_f32 v154, v64, v65
	v_cvt_pk_bf16_f32 v155, v66, v67
	global_store_dwordx2 v[150:151], v[154:155], off offset:288
	global_load_dwordx4 v[154:157], v[160:161], off nt
	v_lshl_add_u64 v[150:151], v[158:159], 1, s[0:1]
	v_lshl_add_u64 v[158:159], v[148:149], 0, s[12:13]
	s_mov_b64 s[12:13], 0x28000
	s_waitcnt vmcnt(0)
	v_pk_fma_f32 v[62:63], v[62:63], v[142:143], v[156:157]
	v_pk_fma_f32 v[60:61], v[60:61], v[140:141], v[154:155]
	s_nop 0
	v_cvt_pk_bf16_f32 v154, v60, v61
	v_cvt_pk_bf16_f32 v155, v62, v63
	global_store_dwordx2 v[150:151], v[154:155], off
	global_load_dwordx4 v[154:157], v[160:161], off offset:64 nt
	s_waitcnt vmcnt(0)
	v_pk_fma_f32 v[58:59], v[58:59], v[138:139], v[156:157]
	v_pk_fma_f32 v[56:57], v[56:57], v[136:137], v[154:155]
	s_nop 0
	v_cvt_pk_bf16_f32 v154, v56, v57
	v_cvt_pk_bf16_f32 v155, v58, v59
	global_store_dwordx2 v[150:151], v[154:155], off offset:32
	global_load_dwordx4 v[154:157], v[160:161], off offset:512 nt
	s_waitcnt vmcnt(0)
	v_pk_fma_f32 v[54:55], v[54:55], v[134:135], v[156:157]
	v_pk_fma_f32 v[52:53], v[52:53], v[132:133], v[154:155]
	s_nop 0
	v_cvt_pk_bf16_f32 v154, v52, v53
	v_cvt_pk_bf16_f32 v155, v54, v55
	global_store_dwordx2 v[150:151], v[154:155], off offset:256
	global_load_dwordx4 v[154:157], v[160:161], off offset:576 nt
	v_lshl_add_u64 v[160:161], v[158:159], 2, s[36:37]
	s_waitcnt vmcnt(0)
	v_pk_fma_f32 v[46:47], v[46:47], v[130:131], v[156:157]
	v_pk_fma_f32 v[44:45], v[44:45], v[128:129], v[154:155]
	s_nop 0
	v_cvt_pk_bf16_f32 v154, v44, v45
	v_cvt_pk_bf16_f32 v155, v46, v47
	global_store_dwordx2 v[150:151], v[154:155], off offset:288
	global_load_dwordx4 v[154:157], v[160:161], off nt
	v_lshl_add_u64 v[150:151], v[158:159], 1, s[0:1]
	v_lshl_add_u64 v[158:159], v[148:149], 0, s[12:13]
	s_mov_b64 s[12:13], 0x2c000
	s_waitcnt vmcnt(0)
	v_pk_fma_f32 v[50:51], v[50:51], v[142:143], v[156:157]
	v_pk_fma_f32 v[48:49], v[48:49], v[140:141], v[154:155]
	s_nop 0
	v_cvt_pk_bf16_f32 v154, v48, v49
	v_cvt_pk_bf16_f32 v155, v50, v51
	global_store_dwordx2 v[150:151], v[154:155], off
	global_load_dwordx4 v[154:157], v[160:161], off offset:64 nt
	s_waitcnt vmcnt(0)
	v_pk_fma_f32 v[42:43], v[42:43], v[138:139], v[156:157]
	v_pk_fma_f32 v[40:41], v[40:41], v[136:137], v[154:155]
	s_nop 0
	v_cvt_pk_bf16_f32 v154, v40, v41
	v_cvt_pk_bf16_f32 v155, v42, v43
	global_store_dwordx2 v[150:151], v[154:155], off offset:32
	global_load_dwordx4 v[154:157], v[160:161], off offset:512 nt
	s_waitcnt vmcnt(0)
	v_pk_fma_f32 v[38:39], v[38:39], v[134:135], v[156:157]
	v_pk_fma_f32 v[36:37], v[36:37], v[132:133], v[154:155]
	s_nop 0
	v_cvt_pk_bf16_f32 v154, v36, v37
	v_cvt_pk_bf16_f32 v155, v38, v39
	global_store_dwordx2 v[150:151], v[154:155], off offset:256
	global_load_dwordx4 v[154:157], v[160:161], off offset:576 nt
	v_lshl_add_u64 v[160:161], v[158:159], 2, s[36:37]
	s_waitcnt vmcnt(0)
; __device__ __forceinline__ unsigned cvt_pk_bf16(float lo, float hi) { unsigned r; asm volatile("v_cvt_pk_bf16_f32 %0, %1, %2" : "=v"(r) : "v"(lo), "v"(hi)); return r; }
;     __device__ __forceinline__ void run(const f32x4 (&v)[2][2][4][2], const Unit& u, int wr, int wc, int fr, int fq, LAS unsigned char* lds, int wid, int lane) const {
;     ...
;         for (int ai = 0; ai < 2; ++ai)
; #pragma unroll
;             for (int m = 0; m < 4; ++m) { float s = 0.f;
; #pragma unroll
;                 for (int bj = 0; bj < 2; ++bj)
; #pragma unroll
;                     for (int n = 0; n < 2; ++n) { const f32x4 x = v[ai][bj][m][n]; s += (x[0] * x[0] + x[1] * x[1]) + (x[2] * x[2] + x[3] * x[3]); }
;                 s += __shfl_xor(s, 16); s += __shfl_xor(s, 32);
;                 if (fq == 0) P[(ai * HALF + wr * 64 + m * 16 + fr) * 4 + wc] = s; }
;     __device__ __forceinline__ void fused(f32x4 (&acc)[2][2][4][2], const Unit& u, int wr, int wc, int fr, int fq, LAS unsigned char* lds, int wid, int lane) const {
;     ...
;           for (int ai = 0; ai < 2; ++ai)
; #pragma unroll
;             for (int m = 0; m < 4; ++m) { const size_t off = (size_t)(row0 + ai * HALF + m * 16) * DM + col0;
; #pragma unroll
;                 for (int bj = 0; bj < 2; ++bj)
; #pragma unroll
;                     for (int n = 0; n < 2; ++n) { const f32x4 xv = *(const f32x4*)(base + off + bj * HALF + n * 16); const f32x4 o = xv + gv[bj][n] * acc[ai][bj][m][n];
;                         u32x2 w; w.x = cvt_pk_bf16(o[0], o[1]); w.y = cvt_pk_bf16(o[2], o[3]); *(u32x2*)(x1b + off + bj * HALF + n * 16) = w; acc[ai][bj][m][n] = o; }
;                 asm volatile("" ::: "memory"); } }
	v_pk_fma_f32 v[30:31], v[30:31], v[130:131], v[156:157]
	v_pk_fma_f32 v[28:29], v[28:29], v[128:129], v[154:155]
	s_nop 0
	v_cvt_pk_bf16_f32 v154, v28, v29
	v_cvt_pk_bf16_f32 v155, v30, v31
	global_store_dwordx2 v[150:151], v[154:155], off offset:288
	global_load_dwordx4 v[154:157], v[160:161], off nt
	v_lshl_add_u64 v[150:151], v[158:159], 1, s[0:1]
	v_lshl_add_u64 v[158:159], v[148:149], 0, s[12:13]
	s_waitcnt vmcnt(0)
	v_pk_fma_f32 v[34:35], v[34:35], v[142:143], v[156:157]
	v_pk_fma_f32 v[32:33], v[32:33], v[140:141], v[154:155]
	s_nop 0
	v_cvt_pk_bf16_f32 v154, v32, v33
	v_cvt_pk_bf16_f32 v155, v34, v35
	global_store_dwordx2 v[150:151], v[154:155], off
	global_load_dwordx4 v[154:157], v[160:161], off offset:64 nt
	s_waitcnt vmcnt(0)
	v_pk_fma_f32 v[26:27], v[26:27], v[138:139], v[156:157]
	v_pk_fma_f32 v[24:25], v[24:25], v[136:137], v[154:155]
	s_nop 0
	v_cvt_pk_bf16_f32 v154, v24, v25
	v_cvt_pk_bf16_f32 v155, v26, v27
	global_store_dwordx2 v[150:151], v[154:155], off offset:32
	global_load_dwordx4 v[154:157], v[160:161], off offset:512 nt
	s_waitcnt vmcnt(0)
	v_pk_fma_f32 v[22:23], v[22:23], v[134:135], v[156:157]
	v_pk_fma_f32 v[20:21], v[20:21], v[132:133], v[154:155]
	s_nop 0
	v_cvt_pk_bf16_f32 v154, v20, v21
	v_cvt_pk_bf16_f32 v155, v22, v23
	global_store_dwordx2 v[150:151], v[154:155], off offset:256
	global_load_dwordx4 v[154:157], v[160:161], off offset:576 nt
	v_lshl_add_u64 v[160:161], v[158:159], 2, s[36:37]
	s_waitcnt vmcnt(0)
	v_pk_fma_f32 v[14:15], v[14:15], v[130:131], v[156:157]
	v_pk_fma_f32 v[12:13], v[12:13], v[128:129], v[154:155]
	v_lshl_add_u64 v[154:155], v[158:159], 1, s[0:1]
	v_cvt_pk_bf16_f32 v148, v12, v13
	v_cvt_pk_bf16_f32 v149, v14, v15
	global_store_dwordx2 v[150:151], v[148:149], off offset:288
	global_load_dwordx4 v[148:151], v[160:161], off nt
	s_lshl_b32 s0, s7, 2
	s_add_i32 s7, s0, 0
	s_waitcnt vmcnt(0)
	v_pk_fma_f32 v[142:143], v[18:19], v[142:143], v[150:151]
	v_pk_fma_f32 v[140:141], v[16:17], v[140:141], v[148:149]
	s_nop 0
	v_cvt_pk_bf16_f32 v16, v140, v141
	v_cvt_pk_bf16_f32 v17, v142, v143
	global_store_dwordx2 v[154:155], v[16:17], off
	global_load_dwordx4 v[148:151], v[160:161], off offset:64 nt
	s_waitcnt vmcnt(0)
	v_pk_fma_f32 v[16:17], v[10:11], v[138:139], v[150:151]
	v_pk_fma_f32 v[18:19], v[8:9], v[136:137], v[148:149]
	s_nop 0
	v_cvt_pk_bf16_f32 v8, v18, v19
	v_cvt_pk_bf16_f32 v9, v16, v17
	global_store_dwordx2 v[154:155], v[8:9], off offset:32
	global_load_dwordx4 v[136:139], v[160:161], off offset:512 nt
	s_waitcnt vmcnt(0)
	v_pk_fma_f32 v[8:9], v[6:7], v[134:135], v[138:139]
	v_pk_fma_f32 v[10:11], v[4:5], v[132:133], v[136:137]
	v_mul_f32_e32 v7, v127, v127
	v_cvt_pk_bf16_f32 v4, v10, v11
	v_cvt_pk_bf16_f32 v5, v8, v9
	global_store_dwordx2 v[154:155], v[4:5], off offset:256
	global_load_dwordx4 v[136:139], v[160:161], off offset:576 nt
	v_mbcnt_lo_u32_b32 v4, -1, 0
	v_mbcnt_hi_u32_b32 v4, -1, v4
	v_and_b32_e32 v6, 64, v4
	v_xor_b32_e32 v5, 16, v4
	v_add_u32_e32 v6, 64, v6
	v_cmp_lt_i32_e32 vcc, v5, v6
	v_fmac_f32_e32 v7, v126, v126
	v_mul_f32_e32 v134, v123, v123
	v_cndmask_b32_e32 v5, v4, v5, vcc
	v_lshlrev_b32_e32 v133, 2, v5
	v_mul_f32_e32 v5, v125, v125
	v_fmac_f32_e32 v5, v124, v124
	v_add_f32_e32 v5, v5, v7
	v_mul_f32_e32 v7, v121, v121
	v_fmac_f32_e32 v7, v120, v120
	v_fmac_f32_e32 v134, v122, v122
	v_add_f32_e32 v7, v7, v134
	v_add_f32_e32 v5, v5, v7
	v_mul_f32_e32 v7, v117, v117
	v_mul_f32_e32 v134, v119, v119
	v_fmac_f32_e32 v7, v116, v116
	v_fmac_f32_e32 v134, v118, v118
	v_add_f32_e32 v7, v7, v134
	v_add_f32_e32 v5, v5, v7
	v_mul_f32_e32 v7, v109, v109
	v_mul_f32_e32 v134, v111, v111
	v_fmac_f32_e32 v7, v108, v108
	v_fmac_f32_e32 v134, v110, v110
	v_add_f32_e32 v7, v7, v134
	v_add_f32_e32 v5, v5, v7
	ds_bpermute_b32 v7, v133, v5
	v_xor_b32_e32 v134, 32, v4
	v_cmp_lt_i32_e32 vcc, v134, v6
	v_and_b32_e32 v132, 63, v170
	s_waitcnt lgkmcnt(0)
	v_add_f32_e32 v135, v5, v7
	v_cndmask_b32_e32 v4, v4, v134, vcc
	v_lshlrev_b32_e32 v134, 2, v4
	v_cmp_gt_u32_e32 vcc, 16, v132
	s_waitcnt vmcnt(0)
	v_pk_fma_f32 v[6:7], v[0:1], v[128:129], v[136:137]
	s_nop 0
	v_cvt_pk_bf16_f32 v0, v6, v7
	v_pk_fma_f32 v[4:5], v[2:3], v[130:131], v[138:139]
	s_nop 0
	v_cvt_pk_bf16_f32 v1, v4, v5
	global_store_dwordx2 v[154:155], v[0:1], off offset:288
	ds_bpermute_b32 v0, v134, v135
	s_and_saveexec_b64 s[0:1], vcc
	v_readlane_b32 s56, v240, 6
	v_readlane_b32 s58, v240, 8
	v_readlane_b32 s57, v240, 7
	v_readlane_b32 s59, v240, 9
	s_cbranch_execz .LBB0_584
	s_lshl_b32 s11, s51, 10
	s_add_i32 s11, s7, s11
	v_lshl_add_u32 v1, v153, 4, s11
	s_waitcnt lgkmcnt(0)
	v_add_f32_e32 v0, v135, v0
	ds_write_b32 v1, v0
